# qk-norm: rotation sign folded into the row's sine values (16 fewer vector multiplies per row, bit-exact)
# speedup vs baseline: 1.0100x; 1.0036x over previous
; __device__ __forceinline__ u16 f2bf(float x) { return (u16)(cvtpk(x, 0.f) & 0xffffu); }
; #define wave_sum(v) wave_sum_l((v), lane)
; __device__ __forceinline__ void qknorm_phase(const Params& p, int ja, int tid, int bid) {
;     ...
;     float cs = 1.f, sn = 0.f;
;     if (lat) { const float pos = (float)(lane < 32 ? (t >> 6) : (t & 63)); sincosf(pos * invf, &sn, &cs); }
;     u16* qr = QKV + (size_t)row * 1536;
;     u16* kdst = KB + ((size_t)(b * 2) * NKEY + key) * 128;
;     unsigned xr1[10], xr2[10];
; #pragma unroll
;     for (int hs = 0; hs < 10; ++hs) { xr1[hs] = qr[hs * 128 + lane]; xr2[hs] = qr[hs * 128 + 64 + lane]; }
;     const u32x2 vraw = *(const u32x2*)(qr + 1280 + lane * 4);
; #pragma unroll
;     for (int hs = 0; hs < 10; ++hs) {
;       const float x1 = __uint_as_float(xr1[hs] << 16), x2 = __uint_as_float(xr2[hs] << 16);
;       const float ss = wave_sum(x1 * x1 + x2 * x2);
;       const float rstd = rsqrtf(ss * (1.f / 128.f) + EPSN);
;       const float y1 = x1 * rstd * (hs < 8 ? qg1 : kg1), y2 = x2 * rstd * (hs < 8 ? qg2 : kg2);
;       const float o1 = y1 * cs - y2 * sn, o2 = y1 * sn + y2 * cs;
;       if (hs < 8) { qr[hs * 128 + lane] = f2bf(o1); qr[hs * 128 + 64 + lane] = f2bf(o2); }
;       else { u16* kd2 = kdst + (size_t)(hs - 8) * NKEY * 128; kd2[lane] = f2bf(o1); kd2[64 + lane] = f2bf(o2); }
.Lq3_wd0:
	v_mul_f32_e32 v64, v7, v64
	v_mul_f32_e32 v65, v7, v65
	v_mul_f32_e32 v66, v7, v66
	v_mul_f32_e32 v67, v7, v67
	v_mul_f32_e32 v68, v7, v68
	v_mul_f32_e32 v69, v7, v69
	v_mul_f32_e32 v70, v7, v70
	v_mul_f32_e32 v71, v7, v71
	v_lshlrev_b32_e32 v72, 16, v32
	v_and_b32_e32 v73, 0xffff0000, v32
	v_lshlrev_b32_e32 v74, 16, v33
	v_and_b32_e32 v75, 0xffff0000, v33
	v_lshlrev_b32_e32 v76, 16, v34
	v_and_b32_e32 v77, 0xffff0000, v34
	v_lshlrev_b32_e32 v78, 16, v35
	v_and_b32_e32 v79, 0xffff0000, v35
	v_mul_f32_e32 v96, v72, v72
	v_fmac_f32_e32 v96, v73, v73
	v_fmac_f32_e32 v96, v74, v74
	v_fmac_f32_e32 v96, v75, v75
	v_fmac_f32_e32 v96, v76, v76
	v_fmac_f32_e32 v96, v77, v77
	v_fmac_f32_e32 v96, v78, v78
	v_fmac_f32_e32 v96, v79, v79
	s_nop 1
	v_add_f32_dpp v96, v96, v96 quad_perm:[1,0,3,2] row_mask:0xf bank_mask:0xf
	s_nop 1
	v_add_f32_dpp v96, v96, v96 quad_perm:[2,3,0,1] row_mask:0xf bank_mask:0xf
	s_nop 1
	v_add_f32_dpp v96, v96, v96 row_half_mirror row_mask:0xf bank_mask:0xf
	s_nop 1
	v_add_f32_dpp v96, v96, v96 row_mirror row_mask:0xf bank_mask:0xf
	s_nop 1
	v_fmamk_f32 v96, v96, 0x3c000000, v202
	v_rsq_f32_e32 v96, v96
	s_nop 0
	v_mul_f32_e32 v80, v96, v72
	v_mul_f32_e32 v81, v96, v73
	v_mul_f32_e32 v82, v96, v74
	v_mul_f32_e32 v83, v96, v75
	v_mul_f32_e32 v84, v96, v76
	v_mul_f32_e32 v85, v96, v77
	v_mul_f32_e32 v86, v96, v78
	v_mul_f32_e32 v87, v96, v79
	v_mul_f32_e32 v80, v16, v80
	v_mul_f32_e32 v81, v17, v81
	v_mul_f32_e32 v82, v18, v82
	v_mul_f32_e32 v83, v19, v83
	v_mul_f32_e32 v84, v20, v84
	v_mul_f32_e32 v85, v21, v85
	v_mul_f32_e32 v86, v22, v86
	v_mul_f32_e32 v87, v23, v87
	s_nop 0
	v_mov_b32_dpp v88, v80 row_ror:8 row_mask:0xf bank_mask:0xf
	v_mov_b32_dpp v89, v81 row_ror:8 row_mask:0xf bank_mask:0xf
	v_mov_b32_dpp v90, v82 row_ror:8 row_mask:0xf bank_mask:0xf
	v_mov_b32_dpp v91, v83 row_ror:8 row_mask:0xf bank_mask:0xf
	v_mov_b32_dpp v92, v84 row_ror:8 row_mask:0xf bank_mask:0xf
	v_mov_b32_dpp v93, v85 row_ror:8 row_mask:0xf bank_mask:0xf
	v_mov_b32_dpp v94, v86 row_ror:8 row_mask:0xf bank_mask:0xf
	v_mov_b32_dpp v95, v87 row_ror:8 row_mask:0xf bank_mask:0xf
	v_mul_f32_e32 v88, v64, v88
	v_mul_f32_e32 v89, v65, v89
	v_mul_f32_e32 v90, v66, v90
	v_mul_f32_e32 v91, v67, v91
	v_mul_f32_e32 v92, v68, v92
	v_mul_f32_e32 v93, v69, v93
	v_mul_f32_e32 v94, v70, v94
	v_mul_f32_e32 v95, v71, v95
	v_fmac_f32_e32 v88, v56, v80
	v_fmac_f32_e32 v89, v57, v81
	v_fmac_f32_e32 v90, v58, v82
	v_fmac_f32_e32 v91, v59, v83
	v_fmac_f32_e32 v92, v60, v84
	v_fmac_f32_e32 v93, v61, v85
	v_fmac_f32_e32 v94, v62, v86
	v_fmac_f32_e32 v95, v63, v87
	v_cvt_pk_bf16_f32 v104, v88, v89
	v_cvt_pk_bf16_f32 v105, v90, v91
	v_cvt_pk_bf16_f32 v106, v92, v93
	v_cvt_pk_bf16_f32 v107, v94, v95
	global_store_dwordx4 v5, v[104:107], s[8:9] offset:0
	v_lshlrev_b32_e32 v72, 16, v36
	v_and_b32_e32 v73, 0xffff0000, v36
	v_lshlrev_b32_e32 v74, 16, v37
	v_and_b32_e32 v75, 0xffff0000, v37
	v_lshlrev_b32_e32 v76, 16, v38
	v_and_b32_e32 v77, 0xffff0000, v38
	v_lshlrev_b32_e32 v78, 16, v39
	v_and_b32_e32 v79, 0xffff0000, v39
	v_mul_f32_e32 v96, v72, v72
	v_fmac_f32_e32 v96, v73, v73
	v_fmac_f32_e32 v96, v74, v74
	v_fmac_f32_e32 v96, v75, v75
	v_fmac_f32_e32 v96, v76, v76
	v_fmac_f32_e32 v96, v77, v77
	v_fmac_f32_e32 v96, v78, v78
	v_fmac_f32_e32 v96, v79, v79
	s_nop 1
	v_add_f32_dpp v96, v96, v96 quad_perm:[1,0,3,2] row_mask:0xf bank_mask:0xf
	s_nop 1
	v_add_f32_dpp v96, v96, v96 quad_perm:[2,3,0,1] row_mask:0xf bank_mask:0xf
	s_nop 1
	v_add_f32_dpp v96, v96, v96 row_half_mirror row_mask:0xf bank_mask:0xf
	s_nop 1
	v_add_f32_dpp v96, v96, v96 row_mirror row_mask:0xf bank_mask:0xf
	s_nop 1
	v_fmamk_f32 v96, v96, 0x3c000000, v202
	v_rsq_f32_e32 v96, v96
	s_nop 0
	v_mul_f32_e32 v80, v96, v72
	v_mul_f32_e32 v81, v96, v73
	v_mul_f32_e32 v82, v96, v74
	v_mul_f32_e32 v83, v96, v75
	v_mul_f32_e32 v84, v96, v76
	v_mul_f32_e32 v85, v96, v77
	v_mul_f32_e32 v86, v96, v78
	v_mul_f32_e32 v87, v96, v79
	v_mul_f32_e32 v80, v16, v80
	v_mul_f32_e32 v81, v17, v81
	v_mul_f32_e32 v82, v18, v82
	v_mul_f32_e32 v83, v19, v83
	v_mul_f32_e32 v84, v20, v84
; __device__ __forceinline__ u16 f2bf(float x) { return (u16)(cvtpk(x, 0.f) & 0xffffu); }
; #define wave_sum(v) wave_sum_l((v), lane)
; __device__ __forceinline__ void qknorm_phase(const Params& p, int ja, int tid, int bid) {
;     ...
; #pragma unroll
;     for (int hs = 0; hs < 10; ++hs) { xr1[hs] = qr[hs * 128 + lane]; xr2[hs] = qr[hs * 128 + 64 + lane]; }
;     const u32x2 vraw = *(const u32x2*)(qr + 1280 + lane * 4);
; #pragma unroll
;     for (int hs = 0; hs < 10; ++hs) {
;       const float x1 = __uint_as_float(xr1[hs] << 16), x2 = __uint_as_float(xr2[hs] << 16);
;       const float ss = wave_sum(x1 * x1 + x2 * x2);
;       const float rstd = rsqrtf(ss * (1.f / 128.f) + EPSN);
;       const float y1 = x1 * rstd * (hs < 8 ? qg1 : kg1), y2 = x2 * rstd * (hs < 8 ? qg2 : kg2);
;       const float o1 = y1 * cs - y2 * sn, o2 = y1 * sn + y2 * cs;
;       if (hs < 8) { qr[hs * 128 + lane] = f2bf(o1); qr[hs * 128 + 64 + lane] = f2bf(o2); }
;       else { u16* kd2 = kdst + (size_t)(hs - 8) * NKEY * 128; kd2[lane] = f2bf(o1); kd2[64 + lane] = f2bf(o2); }
;     }
;     *(u32x2*)(VB + ((size_t)(b * 2 + (lane >> 5)) * NKEY + key) * 128 + (lane & 31) * 4) = vraw;
	v_mul_f32_e32 v85, v21, v85
	v_mul_f32_e32 v86, v22, v86
	v_mul_f32_e32 v87, v23, v87
	s_nop 0
	v_mov_b32_dpp v88, v80 row_ror:8 row_mask:0xf bank_mask:0xf
	v_mov_b32_dpp v89, v81 row_ror:8 row_mask:0xf bank_mask:0xf
	v_mov_b32_dpp v90, v82 row_ror:8 row_mask:0xf bank_mask:0xf
	v_mov_b32_dpp v91, v83 row_ror:8 row_mask:0xf bank_mask:0xf
	v_mov_b32_dpp v92, v84 row_ror:8 row_mask:0xf bank_mask:0xf
	v_mov_b32_dpp v93, v85 row_ror:8 row_mask:0xf bank_mask:0xf
	v_mov_b32_dpp v94, v86 row_ror:8 row_mask:0xf bank_mask:0xf
	v_mov_b32_dpp v95, v87 row_ror:8 row_mask:0xf bank_mask:0xf
	v_mul_f32_e32 v88, v64, v88
	v_mul_f32_e32 v89, v65, v89
	v_mul_f32_e32 v90, v66, v90
	v_mul_f32_e32 v91, v67, v91
	v_mul_f32_e32 v92, v68, v92
	v_mul_f32_e32 v93, v69, v93
	v_mul_f32_e32 v94, v70, v94
	v_mul_f32_e32 v95, v71, v95
	v_fmac_f32_e32 v88, v56, v80
	v_fmac_f32_e32 v89, v57, v81
	v_fmac_f32_e32 v90, v58, v82
	v_fmac_f32_e32 v91, v59, v83
	v_fmac_f32_e32 v92, v60, v84
	v_fmac_f32_e32 v93, v61, v85
	v_fmac_f32_e32 v94, v62, v86
	v_fmac_f32_e32 v95, v63, v87
	v_cvt_pk_bf16_f32 v104, v88, v89
	v_cvt_pk_bf16_f32 v105, v90, v91
	v_cvt_pk_bf16_f32 v106, v92, v93
	v_cvt_pk_bf16_f32 v107, v94, v95
	global_store_dwordx4 v5, v[104:107], s[8:9] offset:1024
	v_lshlrev_b32_e32 v72, 16, v40
	v_and_b32_e32 v73, 0xffff0000, v40
	v_lshlrev_b32_e32 v74, 16, v41
	v_and_b32_e32 v75, 0xffff0000, v41
	v_lshlrev_b32_e32 v76, 16, v42
	v_and_b32_e32 v77, 0xffff0000, v42
	v_lshlrev_b32_e32 v78, 16, v43
	v_and_b32_e32 v79, 0xffff0000, v43
	v_mul_f32_e32 v96, v72, v72
	v_fmac_f32_e32 v96, v73, v73
	v_fmac_f32_e32 v96, v74, v74
	v_fmac_f32_e32 v96, v75, v75
	v_fmac_f32_e32 v96, v76, v76
	v_fmac_f32_e32 v96, v77, v77
	v_fmac_f32_e32 v96, v78, v78
	v_fmac_f32_e32 v96, v79, v79
	s_nop 1
	v_add_f32_dpp v96, v96, v96 quad_perm:[1,0,3,2] row_mask:0xf bank_mask:0xf
	s_nop 1
	v_add_f32_dpp v96, v96, v96 quad_perm:[2,3,0,1] row_mask:0xf bank_mask:0xf
	s_nop 1
	v_add_f32_dpp v96, v96, v96 row_half_mirror row_mask:0xf bank_mask:0xf
	s_nop 1
	v_add_f32_dpp v96, v96, v96 row_mirror row_mask:0xf bank_mask:0xf
	s_nop 1
	v_fmamk_f32 v96, v96, 0x3c000000, v202
	v_rsq_f32_e32 v96, v96
	s_nop 0
	v_mul_f32_e32 v80, v96, v72
	v_mul_f32_e32 v81, v96, v73
	v_mul_f32_e32 v82, v96, v74
	v_mul_f32_e32 v83, v96, v75
	v_mul_f32_e32 v84, v96, v76
	v_mul_f32_e32 v85, v96, v77
	v_mul_f32_e32 v86, v96, v78
	v_mul_f32_e32 v87, v96, v79
	v_mul_f32_e32 v80, v24, v80
	v_mul_f32_e32 v81, v25, v81
	v_mul_f32_e32 v82, v26, v82
	v_mul_f32_e32 v83, v27, v83
	v_mul_f32_e32 v84, v28, v84
	v_mul_f32_e32 v85, v29, v85
	v_mul_f32_e32 v86, v30, v86
	v_mul_f32_e32 v87, v31, v87
	s_nop 0
	v_mov_b32_dpp v88, v80 row_ror:8 row_mask:0xf bank_mask:0xf
	v_mov_b32_dpp v89, v81 row_ror:8 row_mask:0xf bank_mask:0xf
	v_mov_b32_dpp v90, v82 row_ror:8 row_mask:0xf bank_mask:0xf
	v_mov_b32_dpp v91, v83 row_ror:8 row_mask:0xf bank_mask:0xf
	v_mov_b32_dpp v92, v84 row_ror:8 row_mask:0xf bank_mask:0xf
	v_mov_b32_dpp v93, v85 row_ror:8 row_mask:0xf bank_mask:0xf
	v_mov_b32_dpp v94, v86 row_ror:8 row_mask:0xf bank_mask:0xf
	v_mov_b32_dpp v95, v87 row_ror:8 row_mask:0xf bank_mask:0xf
	v_mul_f32_e32 v88, v64, v88
	v_mul_f32_e32 v89, v65, v89
	v_mul_f32_e32 v90, v66, v90
	v_mul_f32_e32 v91, v67, v91
	v_mul_f32_e32 v92, v68, v92
	v_mul_f32_e32 v93, v69, v93
	v_mul_f32_e32 v94, v70, v94
	v_mul_f32_e32 v95, v71, v95
	v_fmac_f32_e32 v88, v56, v80
	v_fmac_f32_e32 v89, v57, v81
	v_fmac_f32_e32 v90, v58, v82
	v_fmac_f32_e32 v91, v59, v83
	v_fmac_f32_e32 v92, v60, v84
	v_fmac_f32_e32 v93, v61, v85
	v_fmac_f32_e32 v94, v62, v86
	v_fmac_f32_e32 v95, v63, v87
	v_cvt_pk_bf16_f32 v104, v88, v89
	v_cvt_pk_bf16_f32 v105, v90, v91
	v_cvt_pk_bf16_f32 v106, v92, v93
	v_cvt_pk_bf16_f32 v107, v94, v95
	v_cndmask_b32_e64 v104, v104, v40, s[22:23]
	v_cndmask_b32_e64 v105, v105, v41, s[22:23]
	v_cndmask_b32_e64 v106, v106, v42, s[22:23]
	v_cndmask_b32_e64 v107, v107, v43, s[22:23]
	global_store_dwordx4 v6, v[104:107], s[4:5]
	s_cmp_lt_u32 s7, 0x8800
	s_cbranch_scc0 .Lq3_done
	s_mov_b32 s6, s7
	s_mov_b32 s8, s10
	s_mov_b32 s9, s11

; __device__ __forceinline__ u16 f2bf(float x) { return (u16)(cvtpk(x, 0.f) & 0xffffu); }
; #define wave_sum(v) wave_sum_l((v), lane)
; __device__ __forceinline__ void qknorm_phase(const Params& p, int ja, int tid, int bid) {
;     ...
;     float cs = 1.f, sn = 0.f;
;     if (lat) { const float pos = (float)(lane < 32 ? (t >> 6) : (t & 63)); sincosf(pos * invf, &sn, &cs); }
;     u16* qr = QKV + (size_t)row * 1536;
;     u16* kdst = KB + ((size_t)(b * 2) * NKEY + key) * 128;
;     unsigned xr1[10], xr2[10];
; #pragma unroll
;     for (int hs = 0; hs < 10; ++hs) { xr1[hs] = qr[hs * 128 + lane]; xr2[hs] = qr[hs * 128 + 64 + lane]; }
;     const u32x2 vraw = *(const u32x2*)(qr + 1280 + lane * 4);
; #pragma unroll
;     for (int hs = 0; hs < 10; ++hs) {
;       const float x1 = __uint_as_float(xr1[hs] << 16), x2 = __uint_as_float(xr2[hs] << 16);
;       const float ss = wave_sum(x1 * x1 + x2 * x2);
;       const float rstd = rsqrtf(ss * (1.f / 128.f) + EPSN);
;       const float y1 = x1 * rstd * (hs < 8 ? qg1 : kg1), y2 = x2 * rstd * (hs < 8 ? qg2 : kg2);
;       const float o1 = y1 * cs - y2 * sn, o2 = y1 * sn + y2 * cs;
;       if (hs < 8) { qr[hs * 128 + lane] = f2bf(o1); qr[hs * 128 + 64 + lane] = f2bf(o2); }
;       else { u16* kd2 = kdst + (size_t)(hs - 8) * NKEY * 128; kd2[lane] = f2bf(o1); kd2[64 + lane] = f2bf(o2); }
;     }
;     *(u32x2*)(VB + ((size_t)(b * 2 + (lane >> 5)) * NKEY + key) * 128 + (lane & 31) * 4) = vraw;
.Lq3_wd1:
	v_mul_f32_e32 v64, v7, v64
	v_mul_f32_e32 v65, v7, v65
	v_mul_f32_e32 v66, v7, v66
	v_mul_f32_e32 v67, v7, v67
	v_mul_f32_e32 v68, v7, v68
	v_mul_f32_e32 v69, v7, v69
	v_mul_f32_e32 v70, v7, v70
	v_mul_f32_e32 v71, v7, v71
	v_lshlrev_b32_e32 v72, 16, v44
	v_and_b32_e32 v73, 0xffff0000, v44
	v_lshlrev_b32_e32 v74, 16, v45
	v_and_b32_e32 v75, 0xffff0000, v45
	v_lshlrev_b32_e32 v76, 16, v46
	v_and_b32_e32 v77, 0xffff0000, v46
	v_lshlrev_b32_e32 v78, 16, v47
	v_and_b32_e32 v79, 0xffff0000, v47
	v_mul_f32_e32 v96, v72, v72
	v_fmac_f32_e32 v96, v73, v73
	v_fmac_f32_e32 v96, v74, v74
	v_fmac_f32_e32 v96, v75, v75
	v_fmac_f32_e32 v96, v76, v76
	v_fmac_f32_e32 v96, v77, v77
	v_fmac_f32_e32 v96, v78, v78
	v_fmac_f32_e32 v96, v79, v79
	s_nop 1
	v_add_f32_dpp v96, v96, v96 quad_perm:[1,0,3,2] row_mask:0xf bank_mask:0xf
	s_nop 1
	v_add_f32_dpp v96, v96, v96 quad_perm:[2,3,0,1] row_mask:0xf bank_mask:0xf
	s_nop 1
	v_add_f32_dpp v96, v96, v96 row_half_mirror row_mask:0xf bank_mask:0xf
	s_nop 1
	v_add_f32_dpp v96, v96, v96 row_mirror row_mask:0xf bank_mask:0xf
	s_nop 1
	v_fmamk_f32 v96, v96, 0x3c000000, v202
	v_rsq_f32_e32 v96, v96
	s_nop 0
	v_mul_f32_e32 v80, v96, v72
	v_mul_f32_e32 v81, v96, v73
	v_mul_f32_e32 v82, v96, v74
	v_mul_f32_e32 v83, v96, v75
	v_mul_f32_e32 v84, v96, v76
	v_mul_f32_e32 v85, v96, v77
	v_mul_f32_e32 v86, v96, v78
	v_mul_f32_e32 v87, v96, v79
	v_mul_f32_e32 v80, v16, v80
	v_mul_f32_e32 v81, v17, v81
	v_mul_f32_e32 v82, v18, v82
	v_mul_f32_e32 v83, v19, v83
	v_mul_f32_e32 v84, v20, v84
	v_mul_f32_e32 v85, v21, v85
	v_mul_f32_e32 v86, v22, v86
	v_mul_f32_e32 v87, v23, v87
	s_nop 0
	v_mov_b32_dpp v88, v80 row_ror:8 row_mask:0xf bank_mask:0xf
	v_mov_b32_dpp v89, v81 row_ror:8 row_mask:0xf bank_mask:0xf
	v_mov_b32_dpp v90, v82 row_ror:8 row_mask:0xf bank_mask:0xf
	v_mov_b32_dpp v91, v83 row_ror:8 row_mask:0xf bank_mask:0xf
	v_mov_b32_dpp v92, v84 row_ror:8 row_mask:0xf bank_mask:0xf
	v_mov_b32_dpp v93, v85 row_ror:8 row_mask:0xf bank_mask:0xf
	v_mov_b32_dpp v94, v86 row_ror:8 row_mask:0xf bank_mask:0xf
	v_mov_b32_dpp v95, v87 row_ror:8 row_mask:0xf bank_mask:0xf
	v_mul_f32_e32 v88, v64, v88
	v_mul_f32_e32 v89, v65, v89
	v_mul_f32_e32 v90, v66, v90
	v_mul_f32_e32 v91, v67, v91
	v_mul_f32_e32 v92, v68, v92
	v_mul_f32_e32 v93, v69, v93
	v_mul_f32_e32 v94, v70, v94
	v_mul_f32_e32 v95, v71, v95
	v_fmac_f32_e32 v88, v56, v80
	v_fmac_f32_e32 v89, v57, v81
	v_fmac_f32_e32 v90, v58, v82
	v_fmac_f32_e32 v91, v59, v83
	v_fmac_f32_e32 v92, v60, v84
	v_fmac_f32_e32 v93, v61, v85
	v_fmac_f32_e32 v94, v62, v86
	v_fmac_f32_e32 v95, v63, v87
	v_cvt_pk_bf16_f32 v104, v88, v89
	v_cvt_pk_bf16_f32 v105, v90, v91
	v_cvt_pk_bf16_f32 v106, v92, v93
	v_cvt_pk_bf16_f32 v107, v94, v95
	global_store_dwordx4 v5, v[104:107], s[8:9] offset:0
	v_lshlrev_b32_e32 v72, 16, v48
	v_and_b32_e32 v73, 0xffff0000, v48
	v_lshlrev_b32_e32 v74, 16, v49
	v_and_b32_e32 v75, 0xffff0000, v49
	v_lshlrev_b32_e32 v76, 16, v50
	v_and_b32_e32 v77, 0xffff0000, v50
	v_lshlrev_b32_e32 v78, 16, v51
	v_and_b32_e32 v79, 0xffff0000, v51
	v_mul_f32_e32 v96, v72, v72
	v_fmac_f32_e32 v96, v73, v73
	v_fmac_f32_e32 v96, v74, v74
	v_fmac_f32_e32 v96, v75, v75
	v_fmac_f32_e32 v96, v76, v76
	v_fmac_f32_e32 v96, v77, v77
	v_fmac_f32_e32 v96, v78, v78
	v_fmac_f32_e32 v96, v79, v79
	s_nop 1
	v_add_f32_dpp v96, v96, v96 quad_perm:[1,0,3,2] row_mask:0xf bank_mask:0xf
	s_nop 1
	v_add_f32_dpp v96, v96, v96 quad_perm:[2,3,0,1] row_mask:0xf bank_mask:0xf
	s_nop 1
	v_add_f32_dpp v96, v96, v96 row_half_mirror row_mask:0xf bank_mask:0xf
	s_nop 1
	v_add_f32_dpp v96, v96, v96 row_mirror row_mask:0xf bank_mask:0xf
	s_nop 1
	v_fmamk_f32 v96, v96, 0x3c000000, v202
	v_rsq_f32_e32 v96, v96
	s_nop 0
	v_mul_f32_e32 v80, v96, v72
	v_mul_f32_e32 v81, v96, v73
	v_mul_f32_e32 v82, v96, v74
	v_mul_f32_e32 v83, v96, v75
	v_mul_f32_e32 v84, v96, v76
	v_mul_f32_e32 v85, v96, v77
	v_mul_f32_e32 v86, v96, v78
	v_mul_f32_e32 v87, v96, v79
	v_mul_f32_e32 v80, v16, v80
	v_mul_f32_e32 v81, v17, v81
	v_mul_f32_e32 v82, v18, v82
	v_mul_f32_e32 v83, v19, v83
	v_mul_f32_e32 v84, v20, v84
; __device__ __forceinline__ u16 f2bf(float x) { return (u16)(cvtpk(x, 0.f) & 0xffffu); }
; #define wave_sum(v) wave_sum_l((v), lane)
; __device__ __forceinline__ void qknorm_phase(const Params& p, int ja, int tid, int bid) {
;     ...
; #pragma unroll
;     for (int hs = 0; hs < 10; ++hs) { xr1[hs] = qr[hs * 128 + lane]; xr2[hs] = qr[hs * 128 + 64 + lane]; }
;     const u32x2 vraw = *(const u32x2*)(qr + 1280 + lane * 4);
; #pragma unroll
;     for (int hs = 0; hs < 10; ++hs) {
;       const float x1 = __uint_as_float(xr1[hs] << 16), x2 = __uint_as_float(xr2[hs] << 16);
;       const float ss = wave_sum(x1 * x1 + x2 * x2);
;       const float rstd = rsqrtf(ss * (1.f / 128.f) + EPSN);
;       const float y1 = x1 * rstd * (hs < 8 ? qg1 : kg1), y2 = x2 * rstd * (hs < 8 ? qg2 : kg2);
;       const float o1 = y1 * cs - y2 * sn, o2 = y1 * sn + y2 * cs;
;       if (hs < 8) { qr[hs * 128 + lane] = f2bf(o1); qr[hs * 128 + 64 + lane] = f2bf(o2); }
;       else { u16* kd2 = kdst + (size_t)(hs - 8) * NKEY * 128; kd2[lane] = f2bf(o1); kd2[64 + lane] = f2bf(o2); }
;     }
;     *(u32x2*)(VB + ((size_t)(b * 2 + (lane >> 5)) * NKEY + key) * 128 + (lane & 31) * 4) = vraw;
	v_mul_f32_e32 v85, v21, v85
	v_mul_f32_e32 v86, v22, v86
	v_mul_f32_e32 v87, v23, v87
	s_nop 0
	v_mov_b32_dpp v88, v80 row_ror:8 row_mask:0xf bank_mask:0xf
	v_mov_b32_dpp v89, v81 row_ror:8 row_mask:0xf bank_mask:0xf
	v_mov_b32_dpp v90, v82 row_ror:8 row_mask:0xf bank_mask:0xf
	v_mov_b32_dpp v91, v83 row_ror:8 row_mask:0xf bank_mask:0xf
	v_mov_b32_dpp v92, v84 row_ror:8 row_mask:0xf bank_mask:0xf
	v_mov_b32_dpp v93, v85 row_ror:8 row_mask:0xf bank_mask:0xf
	v_mov_b32_dpp v94, v86 row_ror:8 row_mask:0xf bank_mask:0xf
	v_mov_b32_dpp v95, v87 row_ror:8 row_mask:0xf bank_mask:0xf
	v_mul_f32_e32 v88, v64, v88
	v_mul_f32_e32 v89, v65, v89
	v_mul_f32_e32 v90, v66, v90
	v_mul_f32_e32 v91, v67, v91
	v_mul_f32_e32 v92, v68, v92
	v_mul_f32_e32 v93, v69, v93
	v_mul_f32_e32 v94, v70, v94
	v_mul_f32_e32 v95, v71, v95
	v_fmac_f32_e32 v88, v56, v80
	v_fmac_f32_e32 v89, v57, v81
	v_fmac_f32_e32 v90, v58, v82
	v_fmac_f32_e32 v91, v59, v83
	v_fmac_f32_e32 v92, v60, v84
	v_fmac_f32_e32 v93, v61, v85
	v_fmac_f32_e32 v94, v62, v86
	v_fmac_f32_e32 v95, v63, v87
	v_cvt_pk_bf16_f32 v104, v88, v89
	v_cvt_pk_bf16_f32 v105, v90, v91
	v_cvt_pk_bf16_f32 v106, v92, v93
	v_cvt_pk_bf16_f32 v107, v94, v95
	global_store_dwordx4 v5, v[104:107], s[8:9] offset:1024
	v_lshlrev_b32_e32 v72, 16, v52
	v_and_b32_e32 v73, 0xffff0000, v52
	v_lshlrev_b32_e32 v74, 16, v53
	v_and_b32_e32 v75, 0xffff0000, v53
	v_lshlrev_b32_e32 v76, 16, v54
	v_and_b32_e32 v77, 0xffff0000, v54
	v_lshlrev_b32_e32 v78, 16, v55
	v_and_b32_e32 v79, 0xffff0000, v55
	v_mul_f32_e32 v96, v72, v72
	v_fmac_f32_e32 v96, v73, v73
	v_fmac_f32_e32 v96, v74, v74
	v_fmac_f32_e32 v96, v75, v75
	v_fmac_f32_e32 v96, v76, v76
	v_fmac_f32_e32 v96, v77, v77
	v_fmac_f32_e32 v96, v78, v78
	v_fmac_f32_e32 v96, v79, v79
	s_nop 1
	v_add_f32_dpp v96, v96, v96 quad_perm:[1,0,3,2] row_mask:0xf bank_mask:0xf
	s_nop 1
	v_add_f32_dpp v96, v96, v96 quad_perm:[2,3,0,1] row_mask:0xf bank_mask:0xf
	s_nop 1
	v_add_f32_dpp v96, v96, v96 row_half_mirror row_mask:0xf bank_mask:0xf
	s_nop 1
	v_add_f32_dpp v96, v96, v96 row_mirror row_mask:0xf bank_mask:0xf
	s_nop 1
	v_fmamk_f32 v96, v96, 0x3c000000, v202
	v_rsq_f32_e32 v96, v96
	s_nop 0
	v_mul_f32_e32 v80, v96, v72
	v_mul_f32_e32 v81, v96, v73
	v_mul_f32_e32 v82, v96, v74
	v_mul_f32_e32 v83, v96, v75
	v_mul_f32_e32 v84, v96, v76
	v_mul_f32_e32 v85, v96, v77
	v_mul_f32_e32 v86, v96, v78
	v_mul_f32_e32 v87, v96, v79
	v_mul_f32_e32 v80, v24, v80
	v_mul_f32_e32 v81, v25, v81
	v_mul_f32_e32 v82, v26, v82
	v_mul_f32_e32 v83, v27, v83
	v_mul_f32_e32 v84, v28, v84
	v_mul_f32_e32 v85, v29, v85
	v_mul_f32_e32 v86, v30, v86
	v_mul_f32_e32 v87, v31, v87
	s_nop 0
	v_mov_b32_dpp v88, v80 row_ror:8 row_mask:0xf bank_mask:0xf
	v_mov_b32_dpp v89, v81 row_ror:8 row_mask:0xf bank_mask:0xf
	v_mov_b32_dpp v90, v82 row_ror:8 row_mask:0xf bank_mask:0xf
	v_mov_b32_dpp v91, v83 row_ror:8 row_mask:0xf bank_mask:0xf
	v_mov_b32_dpp v92, v84 row_ror:8 row_mask:0xf bank_mask:0xf
	v_mov_b32_dpp v93, v85 row_ror:8 row_mask:0xf bank_mask:0xf
	v_mov_b32_dpp v94, v86 row_ror:8 row_mask:0xf bank_mask:0xf
	v_mov_b32_dpp v95, v87 row_ror:8 row_mask:0xf bank_mask:0xf
	v_mul_f32_e32 v88, v64, v88
	v_mul_f32_e32 v89, v65, v89
	v_mul_f32_e32 v90, v66, v90
	v_mul_f32_e32 v91, v67, v91
	v_mul_f32_e32 v92, v68, v92
	v_mul_f32_e32 v93, v69, v93
	v_mul_f32_e32 v94, v70, v94
	v_mul_f32_e32 v95, v71, v95
	v_fmac_f32_e32 v88, v56, v80
	v_fmac_f32_e32 v89, v57, v81
	v_fmac_f32_e32 v90, v58, v82
	v_fmac_f32_e32 v91, v59, v83
	v_fmac_f32_e32 v92, v60, v84
	v_fmac_f32_e32 v93, v61, v85
	v_fmac_f32_e32 v94, v62, v86
	v_fmac_f32_e32 v95, v63, v87
	v_cvt_pk_bf16_f32 v104, v88, v89
	v_cvt_pk_bf16_f32 v105, v90, v91
	v_cvt_pk_bf16_f32 v106, v92, v93
	v_cvt_pk_bf16_f32 v107, v94, v95
	v_cndmask_b32_e64 v104, v104, v52, s[22:23]
	v_cndmask_b32_e64 v105, v105, v53, s[22:23]
	v_cndmask_b32_e64 v106, v106, v54, s[22:23]
	v_cndmask_b32_e64 v107, v107, v55, s[22:23]
	global_store_dwordx4 v6, v[104:107], s[4:5]
	s_cmp_lt_u32 s7, 0x8800
	s_cbranch_scc0 .Lq3_done
	s_mov_b32 s6, s7
	s_mov_b32 s8, s10
	s_mov_b32 s9, s11
	s_branch .Lq3_row0
